# MLA work queue: only q-blocks 60..63 (was 58..63) split into 128-query half items
# speedup vs baseline: 1.0122x; 1.0122x over previous
.LBB0_1382:
	s_or_b64 exec, exec, s[16:17]
	s_add_i32 s16, 0, 0x14000
	v_mov_b32_e32 v0, s16
	s_waitcnt lgkmcnt(0)
	s_barrier
	ds_read_b32 v0, v0
	s_movk_i32 s16, 0x197
	s_waitcnt lgkmcnt(0)
	s_barrier
	v_cmp_lt_i32_e32 vcc, s16, v0
	v_readfirstlane_b32 s18, v0
	s_mov_b64 s[16:17], -1
	s_cbranch_vccnz .LBB0_1377
	s_cmp_lt_u32 s18, 0x30
	s_cbranch_scc1 .Lmla_half_item
	s_sub_i32 s18, s18, 0x30
	s_mul_hi_u32 s16, s18, 0x2aaaaaab
	s_sub_i32 s20, 59, s16
	s_mul_i32 s16, s16, 6
	s_sub_i32 s16, s18, s16
	s_mov_b32 s31, 4
	s_mov_b32 s30, s14
	v_lshl_add_u32 v196, s20, 8, v231
	s_branch .Lmla_item_ready
